# P5/P9 out-projection epilogues: v_permlane16_swap pairs n=0/n=1 fragments so each lane stores 16 contiguous bytes (16 dwordx4 instead of 32 dwordx2 stores per unit)
# speedup vs baseline: 1.1970x; 1.0098x over previous
.LBB0_477:
	v_lshl_add_u32 v2, s58, 8, v224
	s_waitcnt lgkmcnt(0)
	v_lshl_or_b32 v132, s90, 8, v240
	v_bfe_u32 v138, v240, 2, 1
	v_mul_u32_u24_e32 v138, 24, v138
	v_lshl_add_u32 v136, v132, 1, v138
	v_mov_b32_e32 v137, 0
	v_ashrrev_i32_e32 v3, 31, v2
	v_lshlrev_b64 v[140:141], 12, v[2:3]
	v_lshl_add_u64 v[140:141], s[26:27], 0, v[140:141]
	v_lshl_add_u64 v[140:141], v[140:141], 0, v[136:137]
	v_or_b32_e32 v142, 16, v2
	v_ashrrev_i32_e32 v143, 31, v142
	v_lshlrev_b64 v[142:143], 12, v[142:143]
	v_lshl_add_u64 v[142:143], s[26:27], 0, v[142:143]
	v_lshl_add_u64 v[142:143], v[142:143], 0, v[136:137]
	v_or_b32_e32 v144, 32, v2
	v_ashrrev_i32_e32 v145, 31, v144
	v_lshlrev_b64 v[144:145], 12, v[144:145]
	v_lshl_add_u64 v[144:145], s[26:27], 0, v[144:145]
	v_lshl_add_u64 v[144:145], v[144:145], 0, v[136:137]
	v_or_b32_e32 v146, 48, v2
	v_ashrrev_i32_e32 v147, 31, v146
	v_lshlrev_b64 v[146:147], 12, v[146:147]
	v_lshl_add_u64 v[146:147], s[26:27], 0, v[146:147]
	v_lshl_add_u64 v[146:147], v[146:147], 0, v[136:137]
	v_lshl_add_u64 v[148:149], v[140:141], 0, s[8:9]
	v_lshl_add_u64 v[150:151], v[142:143], 0, s[8:9]
	v_lshl_add_u64 v[152:153], v[144:145], 0, s[8:9]
	v_lshl_add_u64 v[154:155], v[146:147], 0, s[8:9]
	s_nop 7
	v_cvt_pk_bf16_f32 v128, v128, v129
	v_cvt_pk_bf16_f32 v129, v130, v131
	v_cvt_pk_bf16_f32 v130, v124, v125
	v_cvt_pk_bf16_f32 v131, v126, v127
	v_cvt_pk_bf16_f32 v116, v116, v117
	v_cvt_pk_bf16_f32 v117, v118, v119
	v_cvt_pk_bf16_f32 v118, v108, v109
	v_cvt_pk_bf16_f32 v119, v110, v111
	s_nop 1
	v_permlane16_swap_b32_e32 v128, v130
	v_permlane16_swap_b32_e32 v129, v131
	v_permlane16_swap_b32_e32 v116, v118
	v_permlane16_swap_b32_e32 v117, v119
	global_store_dwordx4 v[140:141], v[128:131], off
	global_store_dwordx4 v[140:141], v[116:119], off offset:256
	v_cvt_pk_bf16_f32 v120, v120, v121
	v_cvt_pk_bf16_f32 v121, v122, v123
	v_cvt_pk_bf16_f32 v122, v112, v113
	v_cvt_pk_bf16_f32 v123, v114, v115
	v_cvt_pk_bf16_f32 v100, v100, v101
	v_cvt_pk_bf16_f32 v101, v102, v103
	v_cvt_pk_bf16_f32 v102, v92, v93
	v_cvt_pk_bf16_f32 v103, v94, v95
	s_nop 1
	v_permlane16_swap_b32_e32 v120, v122
	v_permlane16_swap_b32_e32 v121, v123
	v_permlane16_swap_b32_e32 v100, v102
	v_permlane16_swap_b32_e32 v101, v103
	global_store_dwordx4 v[142:143], v[120:123], off
	global_store_dwordx4 v[142:143], v[100:103], off offset:256
	v_cvt_pk_bf16_f32 v104, v104, v105
	v_cvt_pk_bf16_f32 v105, v106, v107
	v_cvt_pk_bf16_f32 v106, v96, v97
	v_cvt_pk_bf16_f32 v107, v98, v99
	v_cvt_pk_bf16_f32 v84, v84, v85
	v_cvt_pk_bf16_f32 v85, v86, v87
	v_cvt_pk_bf16_f32 v86, v76, v77
	v_cvt_pk_bf16_f32 v87, v78, v79
	s_nop 1
	v_permlane16_swap_b32_e32 v104, v106
	v_permlane16_swap_b32_e32 v105, v107
	v_permlane16_swap_b32_e32 v84, v86
	v_permlane16_swap_b32_e32 v85, v87
	global_store_dwordx4 v[144:145], v[104:107], off
	global_store_dwordx4 v[144:145], v[84:87], off offset:256
	v_cvt_pk_bf16_f32 v88, v88, v89
	v_cvt_pk_bf16_f32 v89, v90, v91
	v_cvt_pk_bf16_f32 v90, v80, v81
	v_cvt_pk_bf16_f32 v91, v82, v83
	v_cvt_pk_bf16_f32 v72, v72, v73
	v_cvt_pk_bf16_f32 v73, v74, v75
	v_cvt_pk_bf16_f32 v74, v68, v69
	v_cvt_pk_bf16_f32 v75, v70, v71
	s_nop 1
	v_permlane16_swap_b32_e32 v88, v90
	v_permlane16_swap_b32_e32 v89, v91
	v_permlane16_swap_b32_e32 v72, v74
	v_permlane16_swap_b32_e32 v73, v75
	global_store_dwordx4 v[146:147], v[88:91], off
	global_store_dwordx4 v[146:147], v[72:75], off offset:256
	v_cvt_pk_bf16_f32 v64, v64, v65
	v_cvt_pk_bf16_f32 v65, v66, v67
	v_cvt_pk_bf16_f32 v66, v60, v61
	v_cvt_pk_bf16_f32 v67, v62, v63
	v_cvt_pk_bf16_f32 v56, v56, v57
	v_cvt_pk_bf16_f32 v57, v58, v59
	v_cvt_pk_bf16_f32 v58, v48, v49
	v_cvt_pk_bf16_f32 v59, v50, v51
	s_nop 1
	v_permlane16_swap_b32_e32 v64, v66
	v_permlane16_swap_b32_e32 v65, v67
	v_permlane16_swap_b32_e32 v56, v58
	v_permlane16_swap_b32_e32 v57, v59
	global_store_dwordx4 v[148:149], v[64:67], off
	global_store_dwordx4 v[148:149], v[56:59], off offset:256
	v_cvt_pk_bf16_f32 v52, v52, v53
	v_cvt_pk_bf16_f32 v53, v54, v55
	v_cvt_pk_bf16_f32 v54, v44, v45
	v_cvt_pk_bf16_f32 v55, v46, v47
	v_cvt_pk_bf16_f32 v40, v40, v41
	v_cvt_pk_bf16_f32 v41, v42, v43
	v_cvt_pk_bf16_f32 v42, v32, v33
	v_cvt_pk_bf16_f32 v43, v34, v35
	s_nop 1
	v_permlane16_swap_b32_e32 v52, v54
	v_permlane16_swap_b32_e32 v53, v55
	v_permlane16_swap_b32_e32 v40, v42
	v_permlane16_swap_b32_e32 v41, v43
	global_store_dwordx4 v[150:151], v[52:55], off
	global_store_dwordx4 v[150:151], v[40:43], off offset:256
	v_cvt_pk_bf16_f32 v36, v36, v37
	v_cvt_pk_bf16_f32 v37, v38, v39
	v_cvt_pk_bf16_f32 v38, v28, v29
	v_cvt_pk_bf16_f32 v39, v30, v31
	v_cvt_pk_bf16_f32 v24, v24, v25
	v_cvt_pk_bf16_f32 v25, v26, v27
	v_cvt_pk_bf16_f32 v26, v16, v17
	v_cvt_pk_bf16_f32 v27, v18, v19
	s_nop 1
	v_permlane16_swap_b32_e32 v36, v38
	v_permlane16_swap_b32_e32 v37, v39
	v_permlane16_swap_b32_e32 v24, v26
	v_permlane16_swap_b32_e32 v25, v27
	global_store_dwordx4 v[152:153], v[36:39], off
	global_store_dwordx4 v[152:153], v[24:27], off offset:256
	v_cvt_pk_bf16_f32 v20, v20, v21
	v_cvt_pk_bf16_f32 v21, v22, v23
	v_cvt_pk_bf16_f32 v22, v12, v13
	v_cvt_pk_bf16_f32 v23, v14, v15
	v_cvt_pk_bf16_f32 v8, v8, v9
	v_cvt_pk_bf16_f32 v9, v10, v11
	v_cvt_pk_bf16_f32 v10, v4, v5
	v_cvt_pk_bf16_f32 v11, v6, v7
	s_nop 1
	v_permlane16_swap_b32_e32 v20, v22
	v_permlane16_swap_b32_e32 v21, v23
	v_permlane16_swap_b32_e32 v8, v10
	v_permlane16_swap_b32_e32 v9, v11
	global_store_dwordx4 v[154:155], v[20:23], off
	global_store_dwordx4 v[154:155], v[8:11], off offset:256
	s_and_b64 vcc, exec, s[44:45]
	s_mov_b32 s90, s89
	s_mov_b32 s58, s46
	s_mov_b64 s[70:71], s[54:55]
	s_mov_b64 s[6:7], s[56:57]
	s_cbranch_vccnz .LBB0_494

.LBB0_911:
	v_lshl_add_u32 v2, s38, 8, v212
	s_waitcnt lgkmcnt(0)
	v_lshl_or_b32 v132, s74, 8, v214
	v_bfe_u32 v138, v214, 2, 1
	v_mul_u32_u24_e32 v138, 24, v138
	v_lshl_add_u32 v136, v132, 1, v138
	v_mov_b32_e32 v137, 0
	v_ashrrev_i32_e32 v3, 31, v2
	v_lshlrev_b64 v[140:141], 12, v[2:3]
	v_lshl_add_u64 v[140:141], s[26:27], 0, v[140:141]
	v_lshl_add_u64 v[140:141], v[140:141], 0, v[136:137]
	v_or_b32_e32 v142, 16, v2
	v_ashrrev_i32_e32 v143, 31, v142
	v_lshlrev_b64 v[142:143], 12, v[142:143]
	v_lshl_add_u64 v[142:143], s[26:27], 0, v[142:143]
	v_lshl_add_u64 v[142:143], v[142:143], 0, v[136:137]
	v_or_b32_e32 v144, 32, v2
	v_ashrrev_i32_e32 v145, 31, v144
	v_lshlrev_b64 v[144:145], 12, v[144:145]
	v_lshl_add_u64 v[144:145], s[26:27], 0, v[144:145]
	v_lshl_add_u64 v[144:145], v[144:145], 0, v[136:137]
	v_or_b32_e32 v146, 48, v2
	v_ashrrev_i32_e32 v147, 31, v146
	v_lshlrev_b64 v[146:147], 12, v[146:147]
	v_lshl_add_u64 v[146:147], s[26:27], 0, v[146:147]
	v_lshl_add_u64 v[146:147], v[146:147], 0, v[136:137]
	v_lshl_add_u64 v[148:149], v[140:141], 0, s[10:11]
	v_lshl_add_u64 v[150:151], v[142:143], 0, s[10:11]
	v_lshl_add_u64 v[152:153], v[144:145], 0, s[10:11]
	v_lshl_add_u64 v[154:155], v[146:147], 0, s[10:11]
	s_nop 7
	v_cvt_pk_bf16_f32 v128, v128, v129
	v_cvt_pk_bf16_f32 v129, v130, v131
	v_cvt_pk_bf16_f32 v130, v124, v125
	v_cvt_pk_bf16_f32 v131, v126, v127
	v_cvt_pk_bf16_f32 v116, v116, v117
	v_cvt_pk_bf16_f32 v117, v118, v119
	v_cvt_pk_bf16_f32 v118, v108, v109
	v_cvt_pk_bf16_f32 v119, v110, v111
	s_nop 1
	v_permlane16_swap_b32_e32 v128, v130
	v_permlane16_swap_b32_e32 v129, v131
	v_permlane16_swap_b32_e32 v116, v118
	v_permlane16_swap_b32_e32 v117, v119
	global_store_dwordx4 v[140:141], v[128:131], off
	global_store_dwordx4 v[140:141], v[116:119], off offset:256
	v_cvt_pk_bf16_f32 v120, v120, v121
	v_cvt_pk_bf16_f32 v121, v122, v123
	v_cvt_pk_bf16_f32 v122, v112, v113
	v_cvt_pk_bf16_f32 v123, v114, v115
	v_cvt_pk_bf16_f32 v100, v100, v101
	v_cvt_pk_bf16_f32 v101, v102, v103
	v_cvt_pk_bf16_f32 v102, v92, v93
	v_cvt_pk_bf16_f32 v103, v94, v95
	s_nop 1
	v_permlane16_swap_b32_e32 v120, v122
	v_permlane16_swap_b32_e32 v121, v123
	v_permlane16_swap_b32_e32 v100, v102
	v_permlane16_swap_b32_e32 v101, v103
	global_store_dwordx4 v[142:143], v[120:123], off
	global_store_dwordx4 v[142:143], v[100:103], off offset:256
	v_cvt_pk_bf16_f32 v104, v104, v105
	v_cvt_pk_bf16_f32 v105, v106, v107
	v_cvt_pk_bf16_f32 v106, v96, v97
	v_cvt_pk_bf16_f32 v107, v98, v99
	v_cvt_pk_bf16_f32 v84, v84, v85
	v_cvt_pk_bf16_f32 v85, v86, v87
	v_cvt_pk_bf16_f32 v86, v76, v77
	v_cvt_pk_bf16_f32 v87, v78, v79
	s_nop 1
	v_permlane16_swap_b32_e32 v104, v106
	v_permlane16_swap_b32_e32 v105, v107
	v_permlane16_swap_b32_e32 v84, v86
	v_permlane16_swap_b32_e32 v85, v87
	global_store_dwordx4 v[144:145], v[104:107], off
	global_store_dwordx4 v[144:145], v[84:87], off offset:256
	v_cvt_pk_bf16_f32 v88, v88, v89
	v_cvt_pk_bf16_f32 v89, v90, v91
	v_cvt_pk_bf16_f32 v90, v80, v81
	v_cvt_pk_bf16_f32 v91, v82, v83
	v_cvt_pk_bf16_f32 v72, v72, v73
	v_cvt_pk_bf16_f32 v73, v74, v75
	v_cvt_pk_bf16_f32 v74, v68, v69
	v_cvt_pk_bf16_f32 v75, v70, v71
	s_nop 1
	v_permlane16_swap_b32_e32 v88, v90
	v_permlane16_swap_b32_e32 v89, v91
	v_permlane16_swap_b32_e32 v72, v74
	v_permlane16_swap_b32_e32 v73, v75
	global_store_dwordx4 v[146:147], v[88:91], off
	global_store_dwordx4 v[146:147], v[72:75], off offset:256
	v_cvt_pk_bf16_f32 v64, v64, v65
	v_cvt_pk_bf16_f32 v65, v66, v67
	v_cvt_pk_bf16_f32 v66, v60, v61
	v_cvt_pk_bf16_f32 v67, v62, v63
	v_cvt_pk_bf16_f32 v56, v56, v57
	v_cvt_pk_bf16_f32 v57, v58, v59
	v_cvt_pk_bf16_f32 v58, v48, v49
	v_cvt_pk_bf16_f32 v59, v50, v51
	s_nop 1
	v_permlane16_swap_b32_e32 v64, v66
	v_permlane16_swap_b32_e32 v65, v67
	v_permlane16_swap_b32_e32 v56, v58
	v_permlane16_swap_b32_e32 v57, v59
	global_store_dwordx4 v[148:149], v[64:67], off
	global_store_dwordx4 v[148:149], v[56:59], off offset:256
	v_cvt_pk_bf16_f32 v52, v52, v53
	v_cvt_pk_bf16_f32 v53, v54, v55
	v_cvt_pk_bf16_f32 v54, v44, v45
	v_cvt_pk_bf16_f32 v55, v46, v47
	v_cvt_pk_bf16_f32 v40, v40, v41
	v_cvt_pk_bf16_f32 v41, v42, v43
	v_cvt_pk_bf16_f32 v42, v32, v33
	v_cvt_pk_bf16_f32 v43, v34, v35
	s_nop 1
	v_permlane16_swap_b32_e32 v52, v54
	v_permlane16_swap_b32_e32 v53, v55
	v_permlane16_swap_b32_e32 v40, v42
	v_permlane16_swap_b32_e32 v41, v43
	global_store_dwordx4 v[150:151], v[52:55], off
	global_store_dwordx4 v[150:151], v[40:43], off offset:256
	v_cvt_pk_bf16_f32 v36, v36, v37
	v_cvt_pk_bf16_f32 v37, v38, v39
	v_cvt_pk_bf16_f32 v38, v28, v29
	v_cvt_pk_bf16_f32 v39, v30, v31
	v_cvt_pk_bf16_f32 v24, v24, v25
	v_cvt_pk_bf16_f32 v25, v26, v27
	v_cvt_pk_bf16_f32 v26, v16, v17
	v_cvt_pk_bf16_f32 v27, v18, v19
	s_nop 1
	v_permlane16_swap_b32_e32 v36, v38
	v_permlane16_swap_b32_e32 v37, v39
	v_permlane16_swap_b32_e32 v24, v26
	v_permlane16_swap_b32_e32 v25, v27
	global_store_dwordx4 v[152:153], v[36:39], off
	global_store_dwordx4 v[152:153], v[24:27], off offset:256
	v_cvt_pk_bf16_f32 v20, v20, v21
	v_cvt_pk_bf16_f32 v21, v22, v23
	v_cvt_pk_bf16_f32 v22, v12, v13
	v_cvt_pk_bf16_f32 v23, v14, v15
	v_cvt_pk_bf16_f32 v8, v8, v9
	v_cvt_pk_bf16_f32 v9, v10, v11
	v_cvt_pk_bf16_f32 v10, v4, v5
	v_cvt_pk_bf16_f32 v11, v6, v7
	s_nop 1
	v_permlane16_swap_b32_e32 v20, v22
	v_permlane16_swap_b32_e32 v21, v23
	v_permlane16_swap_b32_e32 v8, v10
	v_permlane16_swap_b32_e32 v9, v11
	global_store_dwordx4 v[154:155], v[20:23], off
	global_store_dwordx4 v[154:155], v[8:11], off offset:256
	s_and_b64 vcc, exec, s[20:21]
	s_mov_b32 s74, s73
	s_mov_b32 s38, s22
	s_mov_b64 s[52:53], s[28:29]
	s_mov_b64 s[8:9], s[30:31]
	s_cbranch_vccnz .LBB0_928
